# v26: + attention unit prologue k-sum table copy issues all loads before one wait, on top of v25
# baseline (speedup 1.0000x reference)
; #define LAS __attribute__((address_space(3)))
;     ...
;         unsigned kg[2], vg[2];
; #pragma unroll
;     for (int i = 0; i < 2; ++i) { const int pp = (2 * w + i) * 64 + lane; const int kr = pp >> 4, kc = (pp & 15) ^ (kr & 15), vr = pp >> 3, vc = (pp & 7) ^ ((vr >> 1) & 7);
;         kg[i] = (unsigned)(kr * kpitch + kc * 8) * 2u; vg[i] = (unsigned)(vr * vtpitch + vc * 8) * 2u; }
;     asm volatile("s_waitcnt vmcnt(0)" ::: "memory");
;     ATT_LOAD(0, 0);
;     if (ntiles > 1) ATT_LOAD(1, 1);
;     }
;     bf16x8 qf[8];
;     { const bf16_t* qr = Qp + (size_t)(32 * w + ql) * qpitch + 8 * h2;
; #pragma unroll
;       for (int ks = 0; ks < 8; ++ks) qf[ks] = *(const bf16x8*)(qr + 16 * ks); }
;     unsigned selmask = 0xffffffffu;
;     if (MOBA) {
;         if (j > 3) {
;             LAS float* KM = (LAS float*)(lds + ATT_KM);
;             for (int i = tid; i < j * 128; i += 512) KM[i] = kmean_bh[(size_t)(i >> 7) * D + (i & 127)];
.LBB0_365:
	s_lshl_b32 s90, s11, 8
	s_add_u32 s2, s8, s90
	s_addc_u32 s3, s9, 0
	s_lshl_b64 s[2:3], s[2:3], 12
	v_mov_b32_e32 v156, v0
	s_add_u32 s64, s27, s2
	s_addc_u32 s65, s86, s3
	v_readfirstlane_b32 s87, v156
	s_ashr_i32 s2, s87, 6
	v_and_b32_e32 v235, 63, v156
	s_lshl_b32 s4, s2, 7
	v_or_b32_e32 v4, s4, v235
	v_ashrrev_i32_e32 v2, 4, v4
	v_xor_b32_e32 v5, v2, v156
	v_lshlrev_b32_e32 v2, 12, v2
	v_lshlrev_b32_e32 v5, 4, v5
	v_and_or_b32 v10, v5, s92, v2
	v_lshlrev_b32_e32 v5, 4, v156
	v_and_b32_e32 v6, 48, v156
	v_lshlrev_b32_e32 v2, 12, v4
	v_bitop3_b32 v6, v5, v6, s93 bitop3:0x6c
	s_mov_b32 s3, 0xfffb8000
	v_and_or_b32 v2, v2, s3, v6
	v_or_b32_e32 v6, 64, v4
	s_lshl_b32 s3, s2, 11
	v_ashrrev_i32_e32 v7, 4, v6
	s_add_i32 s95, s3, 0
	v_xor_b32_e32 v8, v7, v156
	s_waitcnt vmcnt(0)
	s_mov_b32 m0, s95
	v_lshlrev_b32_e32 v7, 12, v7
	v_lshlrev_b32_e32 v8, 4, v8
	v_lshlrev_b32_e32 v6, 12, v6
	global_load_lds_dwordx4 v10, s[52:53]
	s_add_i32 m0, s95, 0xc000
	v_and_or_b32 v11, v8, s92, v7
	v_and_b32_e32 v6, 0xffff8000, v6
	v_bitop3_b32 v4, v4, v5, 64 bitop3:0x36
	global_load_lds_dwordx4 v2, s[50:51]
	s_add_i32 m0, s95, 0x400
	v_and_or_b32 v4, v4, s93, v6
	global_load_lds_dwordx4 v11, s[52:53]
	s_add_i32 m0, s95, 0xc400
	v_lshl_add_u64 v[6:7], s[50:51], 0, v[2:3]
	v_mov_b32_e32 v5, v3
	global_load_lds_dwordx4 v4, s[50:51]
	s_add_i32 m0, s95, 0x4000
	v_and_b32_e32 v234, 31, v156
	v_lshl_add_u64 v[8:9], s[50:51], 0, v[4:5]
	global_load_lds_dwordx4 v10, s[56:57]
	v_lshl_add_u64 v[4:5], v[6:7], 0, s[62:63]
	s_add_i32 m0, s95, 0x10000
	s_lshl_b32 s96, s2, 5
	global_load_lds_dwordx4 v[4:5], off
	s_add_i32 m0, s95, 0x4400
	v_or_b32_e32 v154, s96, v234
	global_load_lds_dwordx4 v11, s[56:57]
	v_lshl_add_u64 v[4:5], v[8:9], 0, s[62:63]
	s_add_i32 m0, s95, 0x10400
	v_ashrrev_i32_e32 v155, 31, v154
	global_load_lds_dwordx4 v[4:5], off
	v_bfe_u32 v236, v156, 5, 1
	v_lshlrev_b64 v[4:5], 12, v[154:155]
	v_lshl_add_u64 v[4:5], s[64:65], 0, v[4:5]
	v_lshlrev_b32_e32 v2, 4, v236
	v_lshl_add_u64 v[4:5], v[4:5], 0, v[2:3]
	global_load_dwordx4 v[114:117], v[4:5], off
	global_load_dwordx4 v[118:121], v[4:5], off offset:32
	global_load_dwordx4 v[122:125], v[4:5], off offset:64
	global_load_dwordx4 v[126:129], v[4:5], off offset:96
	global_load_dwordx4 v[130:133], v[4:5], off offset:128
	global_load_dwordx4 v[134:137], v[4:5], off offset:160
	global_load_dwordx4 v[138:141], v[4:5], off offset:192
	global_load_dwordx4 v[142:145], v[4:5], off offset:224
	v_lshlrev_b32_e32 v155, 3, v236
	s_cmp_lt_u32 s11, 4
	v_mov_b32_e32 v160, -1
	s_cbranch_scc1 .LBB0_402
	s_mov_b64 s[2:3], exec
	v_lshrrev_b32_e32 v4, 7, v156
	v_and_b32_e32 v2, 0x7f, v156
	v_lshl_add_u32 v6, v156, 2, s37
	v_lshlrev_b32_e32 v2, 2, v2
	v_readfirstlane_b32 s98, v4
	v_lshl_add_u32 v2, v4, 13, v2
	s_nop 3
	global_load_dword v8, v2, s[48:49]
	s_add_u32 s99, s98, 4
	s_cmp_lt_u32 s99, s11
	s_cbranch_scc0 .Lkm_n1
	v_add_u32_e32 v12, 0x8000, v2
	global_load_dword v9, v12, s[48:49]
	s_add_u32 s99, s98, 8
	s_cmp_lt_u32 s99, s11
	s_cbranch_scc0 .Lkm_n2
	v_add_u32_e32 v13, 0x10000, v2
	global_load_dword v10, v13, s[48:49]
	s_add_u32 s99, s98, 12
	s_cmp_lt_u32 s99, s11
	s_cbranch_scc0 .Lkm_n3
	v_add_u32_e32 v14, 0x18000, v2
	global_load_dword v11, v14, s[48:49]
	s_waitcnt vmcnt(0)
	ds_write_b32 v6, v11 offset:6144
.Lkm_n3:
	s_waitcnt vmcnt(0)
	ds_write_b32 v6, v10 offset:4096
.Lkm_n2:
	s_waitcnt vmcnt(0)
	ds_write_b32 v6, v9 offset:2048
.Lkm_n1:
	s_waitcnt vmcnt(0)
	ds_write_b32 v6, v8
